# attention epilogue: gains loaded right after the combine barrier, combine-buffer reads 8 deep, stale vmcnt wait removed
# speedup vs baseline: 1.0085x; 1.0085x over previous
.LBB0_223:
	s_cmp_gt_i32 s6, 3
	s_waitcnt lgkmcnt(0)
	s_barrier
	s_cbranch_scc1 .LBB0_198
	v_lshlrev_b32_e32 v89, 4, v80
	global_load_dwordx4 v[192:195], v89, s[2:3]
	global_load_dwordx4 v[196:199], v89, s[2:3] offset:32
	global_load_dwordx4 v[200:203], v89, s[2:3] offset:64
	global_load_dwordx4 v[204:207], v89, s[2:3] offset:96
	global_load_dwordx4 v[208:211], v89, s[2:3] offset:128
	global_load_dwordx4 v[212:215], v89, s[2:3] offset:160
	global_load_dwordx4 v[216:219], v89, s[2:3] offset:192
	global_load_dwordx4 v[220:223], v89, s[2:3] offset:224
	global_load_dwordx4 v[224:227], v89, s[2:3] offset:256
	global_load_dwordx4 v[228:231], v89, s[2:3] offset:288
	global_load_dwordx4 v[232:235], v89, s[2:3] offset:320
	global_load_dwordx4 v[236:239], v89, s[2:3] offset:352
	global_load_dwordx4 v[244:247], v89, s[2:3] offset:384
	global_load_dwordx4 v[248:251], v89, s[2:3] offset:416
	global_load_dwordx4 v[252:255], v89, s[2:3] offset:448
	global_load_dwordx4 v[148:151], v89, s[2:3] offset:480
	s_lshl_b32 s6, s5, 14
	v_add3_u32 v2, v7, v6, s6
	ds_read2_b32 v[96:97], v2 offset1:32
	ds_read2_b32 v[98:99], v2 offset0:64 offset1:96
	v_add_u32_e32 v88, 0x400, v2
	ds_read2_b32 v[100:101], v88 offset1:32
	ds_read2_b32 v[102:103], v88 offset0:64 offset1:96
	v_add_u32_e32 v88, 0x800, v2
	ds_read2_b32 v[104:105], v88 offset1:32
	ds_read2_b32 v[106:107], v88 offset0:64 offset1:96
	v_add_u32_e32 v88, 0xc00, v2
	ds_read2_b32 v[108:109], v88 offset1:32
	ds_read2_b32 v[110:111], v88 offset0:64 offset1:96
	s_waitcnt lgkmcnt(7)
	v_fma_f32 v81, v64, v0, -v96
	v_fma_f32 v64, v65, v0, -v97
	v_add_u32_e32 v88, 0x1000, v2
	ds_read2_b32 v[96:97], v88 offset1:32
	s_waitcnt lgkmcnt(7)
	v_fma_f32 v65, v66, v0, -v98
	v_fma_f32 v66, v67, v0, -v99
	ds_read2_b32 v[98:99], v88 offset0:64 offset1:96
	v_mul_f32_e32 v6, v64, v64
	v_fmac_f32_e32 v6, v81, v81
	v_fmac_f32_e32 v6, v65, v65
	v_fmac_f32_e32 v6, v66, v66
	s_waitcnt lgkmcnt(7)
	v_fma_f32 v67, v68, v0, -v100
	v_fma_f32 v68, v69, v0, -v101
	v_add_u32_e32 v88, 0x1400, v2
	ds_read2_b32 v[100:101], v88 offset1:32
	v_fmac_f32_e32 v6, v67, v67
	v_fmac_f32_e32 v6, v68, v68
	s_waitcnt lgkmcnt(7)
	v_fma_f32 v69, v70, v0, -v102
	v_fma_f32 v70, v71, v0, -v103
	ds_read2_b32 v[102:103], v88 offset0:64 offset1:96
	v_fmac_f32_e32 v6, v69, v69
	v_fmac_f32_e32 v6, v70, v70
	s_waitcnt lgkmcnt(7)
	v_fma_f32 v72, v72, v0, -v104
	v_fma_f32 v71, v73, v0, -v105
	v_add_u32_e32 v88, 0x1800, v2
	ds_read2_b32 v[104:105], v88 offset1:32
	v_fmac_f32_e32 v6, v72, v72
	v_fmac_f32_e32 v6, v71, v71
	s_waitcnt lgkmcnt(7)
	v_fma_f32 v82, v74, v0, -v106
	v_fma_f32 v75, v75, v0, -v107
	ds_read2_b32 v[106:107], v88 offset0:64 offset1:96
	v_fmac_f32_e32 v6, v82, v82
	v_fmac_f32_e32 v6, v75, v75
	s_waitcnt lgkmcnt(7)
	v_fma_f32 v74, v76, v0, -v108
	v_fma_f32 v73, v77, v0, -v109
	v_add_u32_e32 v88, 0x1c00, v2
	ds_read2_b32 v[108:109], v88 offset1:32
	v_fmac_f32_e32 v6, v74, v74
	v_fmac_f32_e32 v6, v73, v73
	s_waitcnt lgkmcnt(7)
	v_fma_f32 v78, v78, v0, -v110
	v_fma_f32 v77, v79, v0, -v111
	ds_read2_b32 v[110:111], v88 offset0:64 offset1:96
	v_fmac_f32_e32 v6, v78, v78
	v_fmac_f32_e32 v6, v77, v77
	s_waitcnt lgkmcnt(7)
	v_fma_f32 v76, v48, v0, -v96
	v_fma_f32 v48, v49, v0, -v97
	v_add_u32_e32 v88, 0x2000, v2
	ds_read2_b32 v[96:97], v88 offset1:32
	v_fmac_f32_e32 v6, v76, v76
	v_fmac_f32_e32 v6, v48, v48
	s_waitcnt lgkmcnt(7)
	v_fma_f32 v79, v50, v0, -v98
	v_fma_f32 v51, v51, v0, -v99
	ds_read2_b32 v[98:99], v88 offset0:64 offset1:96
	v_fmac_f32_e32 v6, v79, v79
	v_fmac_f32_e32 v6, v51, v51
	s_waitcnt lgkmcnt(7)
	v_fma_f32 v50, v52, v0, -v100
	v_fma_f32 v49, v53, v0, -v101
	v_add_u32_e32 v88, 0x2400, v2
	ds_read2_b32 v[100:101], v88 offset1:32
	v_fmac_f32_e32 v6, v50, v50
	v_fmac_f32_e32 v6, v49, v49
	s_waitcnt lgkmcnt(7)
	v_fma_f32 v83, v54, v0, -v102
	v_fma_f32 v54, v55, v0, -v103
	ds_read2_b32 v[102:103], v88 offset0:64 offset1:96
	v_fmac_f32_e32 v6, v83, v83
	v_fmac_f32_e32 v6, v54, v54
	s_waitcnt lgkmcnt(7)
	v_fma_f32 v53, v56, v0, -v104
	v_fma_f32 v52, v57, v0, -v105
	v_add_u32_e32 v88, 0x2800, v2
	ds_read2_b32 v[104:105], v88 offset1:32
	v_fmac_f32_e32 v6, v53, v53
	v_fmac_f32_e32 v6, v52, v52
	s_waitcnt lgkmcnt(7)
	v_fma_f32 v58, v58, v0, -v106
	v_fma_f32 v57, v59, v0, -v107
	ds_read2_b32 v[106:107], v88 offset0:64 offset1:96
	v_fmac_f32_e32 v6, v58, v58
	v_fmac_f32_e32 v6, v57, v57
	s_waitcnt lgkmcnt(7)
	v_fma_f32 v56, v60, v0, -v108
	v_fma_f32 v55, v61, v0, -v109
	v_add_u32_e32 v88, 0x2c00, v2
	ds_read2_b32 v[108:109], v88 offset1:32
	v_fmac_f32_e32 v6, v56, v56
	v_fmac_f32_e32 v6, v55, v55
	s_waitcnt lgkmcnt(7)
	v_fma_f32 v61, v62, v0, -v110
	v_fma_f32 v60, v63, v0, -v111
	ds_read2_b32 v[110:111], v88 offset0:64 offset1:96
	v_fmac_f32_e32 v6, v61, v61
	v_fmac_f32_e32 v6, v60, v60
	s_waitcnt lgkmcnt(7)
	v_fma_f32 v59, v32, v0, -v96
	v_fma_f32 v32, v33, v0, -v97
	v_add_u32_e32 v88, 0x3000, v2
	ds_read2_b32 v[96:97], v88 offset1:32
	v_fmac_f32_e32 v6, v59, v59
	v_fmac_f32_e32 v6, v32, v32
	s_waitcnt lgkmcnt(7)
	v_fma_f32 v63, v34, v0, -v98
	v_fma_f32 v62, v35, v0, -v99
	ds_read2_b32 v[98:99], v88 offset0:64 offset1:96
	v_fmac_f32_e32 v6, v63, v63
	v_fmac_f32_e32 v6, v62, v62
	s_waitcnt lgkmcnt(7)
	v_fma_f32 v36, v36, v0, -v100
	v_fma_f32 v34, v37, v0, -v101
	v_add_u32_e32 v88, 0x3400, v2
	ds_read2_b32 v[100:101], v88 offset1:32
	v_fmac_f32_e32 v6, v36, v36
	v_fmac_f32_e32 v6, v34, v34
	s_waitcnt lgkmcnt(7)
	v_fma_f32 v85, v38, v0, -v102
	v_fma_f32 v84, v39, v0, -v103
	v_fmac_f32_e32 v6, v85, v85
	v_fmac_f32_e32 v6, v84, v84
	s_waitcnt lgkmcnt(6)
	v_fma_f32 v40, v40, v0, -v104
	v_fma_f32 v39, v41, v0, -v105
	v_fmac_f32_e32 v6, v40, v40
	v_fmac_f32_e32 v6, v39, v39
	s_waitcnt lgkmcnt(5)
	v_fma_f32 v87, v42, v0, -v106
	v_fma_f32 v86, v43, v0, -v107
	v_fmac_f32_e32 v6, v87, v87
	v_fmac_f32_e32 v6, v86, v86
	s_waitcnt lgkmcnt(4)
	v_fma_f32 v44, v44, v0, -v108
	v_fma_f32 v43, v45, v0, -v109
	v_fmac_f32_e32 v6, v44, v44
	v_fmac_f32_e32 v6, v43, v43
	s_waitcnt lgkmcnt(3)
	v_fma_f32 v42, v46, v0, -v110
	v_fma_f32 v41, v47, v0, -v111
	v_fmac_f32_e32 v6, v42, v42
	v_fmac_f32_e32 v6, v41, v41
	s_waitcnt lgkmcnt(2)
	v_fma_f32 v38, v16, v0, -v96
	v_fma_f32 v37, v17, v0, -v97
	v_fmac_f32_e32 v6, v38, v38
	v_fmac_f32_e32 v6, v37, v37
	s_waitcnt lgkmcnt(1)
	v_fma_f32 v35, v18, v0, -v98
	v_fma_f32 v33, v19, v0, -v99
	v_fmac_f32_e32 v6, v35, v35
	v_fmac_f32_e32 v6, v33, v33
	s_waitcnt lgkmcnt(0)
	v_fma_f32 v20, v20, v0, -v100
	v_fma_f32 v19, v21, v0, -v101
	v_fmac_f32_e32 v6, v20, v20
	v_fmac_f32_e32 v6, v19, v19
	v_add_u32_e32 v7, 0x3400, v2
	ds_read2_b32 v[8:9], v7 offset0:64 offset1:96
	v_lshlrev_b32_e32 v21, 4, v80
	s_waitcnt lgkmcnt(0)
	v_pk_fma_f32 v[14:15], v[22:23], v[0:1], v[8:9] op_sel_hi:[1,0,1] neg_lo:[0,0,1] neg_hi:[0,0,1]
	s_nop 0
	v_pk_mul_f32 v[8:9], v[14:15], v[14:15]
	s_nop 0
	v_add_f32_e32 v6, v6, v8
	v_add_f32_e32 v8, v6, v9
	v_add_u32_e32 v9, 0x3800, v2
	ds_read2_b32 v[6:7], v9 offset1:32
	v_add_u32_e32 v2, 0x3c00, v2
	s_waitcnt lgkmcnt(0)
	v_pk_fma_f32 v[12:13], v[24:25], v[0:1], v[6:7] op_sel_hi:[1,0,1] neg_lo:[0,0,1] neg_hi:[0,0,1]
	s_nop 0
	v_pk_mul_f32 v[6:7], v[12:13], v[12:13]
	s_nop 0
	v_add_f32_e32 v6, v8, v6
	v_add_f32_e32 v8, v6, v7
	ds_read2_b32 v[6:7], v9 offset0:64 offset1:96
	s_waitcnt lgkmcnt(0)
	v_pk_fma_f32 v[10:11], v[26:27], v[0:1], v[6:7] op_sel_hi:[1,0,1] neg_lo:[0,0,1] neg_hi:[0,0,1]
	s_nop 0
	v_pk_mul_f32 v[6:7], v[10:11], v[10:11]
	s_nop 0
	v_add_f32_e32 v6, v8, v6
	v_add_f32_e32 v16, v6, v7
	ds_read2_b32 v[6:7], v2 offset1:32
	s_waitcnt lgkmcnt(0)
	v_pk_fma_f32 v[8:9], v[28:29], v[0:1], v[6:7] op_sel_hi:[1,0,1] neg_lo:[0,0,1] neg_hi:[0,0,1]
	s_nop 0
	v_pk_mul_f32 v[6:7], v[8:9], v[8:9]
	s_nop 0
	v_add_f32_e32 v6, v16, v6
	v_add_f32_e32 v18, v6, v7
	ds_read2_b32 v[6:7], v2 offset0:64 offset1:96
	s_waitcnt lgkmcnt(0)
	v_pk_fma_f32 v[6:7], v[30:31], v[0:1], v[6:7] op_sel_hi:[1,0,1] neg_lo:[0,0,1] neg_hi:[0,0,1]
	s_nop 0
	v_pk_mul_f32 v[16:17], v[6:7], v[6:7]
	s_nop 0
	v_add_f32_e32 v0, v18, v16
	v_add_f32_e32 v0, v0, v17
	ds_bpermute_b32 v2, v5, v0
	s_waitcnt lgkmcnt(0)
	v_add_f32_e32 v0, v0, v2
	v_fmamk_f32 v0, v0, 0x3c000000, v174
	v_cmp_gt_f32_e32 vcc, s90, v0
	v_mul_f32_e32 v2, 0x4b800000, v0
	s_nop 0
	v_cndmask_b32_e32 v0, v0, v2, vcc
	v_rsq_f32_e32 v0, v0
	s_nop 0
	v_mul_f32_e32 v2, 0x45800000, v0
	v_cndmask_b32_e32 v0, v0, v2, vcc
	v_mul_f32_e32 v18, v3, v0
	v_lshl_or_b32 v0, s5, 5, v4
	v_or_b32_e32 v0, s22, v0
	v_lshlrev_b64 v[2:3], 11, v[0:1]
	v_lshl_add_u64 v[2:3], s[84:85], 0, v[2:3]
	s_mov_b32 s5, s81
	v_lshl_add_u64 v[16:17], v[2:3], 0, s[4:5]
	s_nop 0
	v_mul_f32_e32 v0, v81, v18
	s_waitcnt vmcnt(0)
	v_mov_b32_e32 v2, v192
	v_mov_b32_e32 v3, v193
	v_mov_b32_e32 v4, v194
	v_mov_b32_e32 v5, v195
	s_nop 0
	v_mul_f32_e32 v0, v2, v0
	v_mul_f32_e32 v2, v64, v18
	v_mul_f32_e32 v2, v3, v2
	v_cvt_pk_bf16_f32 v22, v0, v2
	v_mul_f32_e32 v0, v65, v18
	v_mul_f32_e32 v0, v4, v0
	v_mul_f32_e32 v2, v66, v18
	v_mul_f32_e32 v2, v5, v2
	v_cvt_pk_bf16_f32 v23, v0, v2
	v_lshlrev_b32_e32 v0, 3, v80
	v_lshl_add_u64 v[2:3], v[16:17], 0, v[0:1]
	global_store_dwordx2 v[2:3], v[22:23], off
	s_nop 0
	v_mul_f32_e32 v0, v67, v18
	v_mul_f32_e32 v4, v68, v18
	v_mul_f32_e32 v5, v70, v18
	s_nop 1
	v_mov_b32_e32 v22, v196
	v_mov_b32_e32 v23, v197
	v_mov_b32_e32 v24, v198
	v_mov_b32_e32 v25, v199
	s_nop 0
	v_mul_f32_e32 v0, v22, v0
	v_mul_f32_e32 v4, v23, v4
	v_cvt_pk_bf16_f32 v4, v0, v4
	v_mul_f32_e32 v0, v69, v18
	v_mul_f32_e32 v5, v25, v5
	v_mul_f32_e32 v0, v24, v0
	v_cvt_pk_bf16_f32 v5, v0, v5
	global_store_dwordx2 v[2:3], v[4:5], off offset:16
	s_nop 0
	v_mul_f32_e32 v0, v72, v18
	v_mul_f32_e32 v4, v71, v18
	v_mul_f32_e32 v5, v75, v18
	s_nop 1
	v_mov_b32_e32 v22, v200
	v_mov_b32_e32 v23, v201
	v_mov_b32_e32 v24, v202
	v_mov_b32_e32 v25, v203
	s_nop 0
	v_mul_f32_e32 v0, v22, v0
	v_mul_f32_e32 v4, v23, v4
	v_cvt_pk_bf16_f32 v4, v0, v4
	v_mul_f32_e32 v0, v82, v18
	v_mul_f32_e32 v5, v25, v5
	v_mul_f32_e32 v0, v24, v0
	v_cvt_pk_bf16_f32 v5, v0, v5
	global_store_dwordx2 v[2:3], v[4:5], off offset:32
	s_nop 0
	v_mul_f32_e32 v0, v74, v18
	v_mul_f32_e32 v4, v73, v18
	v_mul_f32_e32 v5, v77, v18
	s_nop 1
	v_mov_b32_e32 v22, v204
	v_mov_b32_e32 v23, v205
	v_mov_b32_e32 v24, v206
	v_mov_b32_e32 v25, v207
	s_nop 0
	v_mul_f32_e32 v0, v0, v22
	v_mul_f32_e32 v4, v4, v23
	v_cvt_pk_bf16_f32 v4, v0, v4
	v_mul_f32_e32 v0, v78, v18
	v_mul_f32_e32 v5, v5, v25
	v_mul_f32_e32 v0, v0, v24
	v_cvt_pk_bf16_f32 v5, v0, v5
	global_store_dwordx2 v[2:3], v[4:5], off offset:48
	s_nop 0
	v_mul_f32_e32 v0, v76, v18
	v_mul_f32_e32 v4, v48, v18
	v_mul_f32_e32 v5, v51, v18
	s_nop 1
	v_mov_b32_e32 v22, v208
	v_mov_b32_e32 v23, v209
	v_mov_b32_e32 v24, v210
	v_mov_b32_e32 v25, v211
	s_nop 0
	v_mul_f32_e32 v0, v0, v22
	v_mul_f32_e32 v4, v4, v23
	v_cvt_pk_bf16_f32 v4, v0, v4
	v_mul_f32_e32 v0, v79, v18
	v_mul_f32_e32 v5, v5, v25
	v_mul_f32_e32 v0, v0, v24
	v_cvt_pk_bf16_f32 v5, v0, v5
	global_store_dwordx2 v[2:3], v[4:5], off offset:64
	s_nop 0
	v_mul_f32_e32 v0, v50, v18
	v_mul_f32_e32 v4, v49, v18
	v_mul_f32_e32 v5, v54, v18
	s_nop 1
	v_mov_b32_e32 v22, v212
	v_mov_b32_e32 v23, v213
	v_mov_b32_e32 v24, v214
	v_mov_b32_e32 v25, v215
	s_nop 0
	v_mul_f32_e32 v0, v0, v22
	v_mul_f32_e32 v4, v4, v23
	v_cvt_pk_bf16_f32 v4, v0, v4
	v_mul_f32_e32 v0, v83, v18
	v_mul_f32_e32 v5, v5, v25
	v_mul_f32_e32 v0, v0, v24
	v_cvt_pk_bf16_f32 v5, v0, v5
	global_store_dwordx2 v[2:3], v[4:5], off offset:80
	s_nop 0
	v_mul_f32_e32 v0, v53, v18
	v_mul_f32_e32 v4, v52, v18
	v_mul_f32_e32 v5, v57, v18
	s_nop 1
	v_mov_b32_e32 v22, v216
	v_mov_b32_e32 v23, v217
	v_mov_b32_e32 v24, v218
	v_mov_b32_e32 v25, v219
	s_nop 0
	v_mul_f32_e32 v0, v0, v22
	v_mul_f32_e32 v4, v4, v23
	v_cvt_pk_bf16_f32 v4, v0, v4
	v_mul_f32_e32 v0, v58, v18
	v_mul_f32_e32 v5, v5, v25
	v_mul_f32_e32 v0, v0, v24
	v_cvt_pk_bf16_f32 v5, v0, v5
	global_store_dwordx2 v[2:3], v[4:5], off offset:96
	s_nop 0
	v_mul_f32_e32 v0, v56, v18
	v_mul_f32_e32 v4, v55, v18
	v_mul_f32_e32 v5, v60, v18
	s_nop 1
	v_mov_b32_e32 v22, v220
	v_mov_b32_e32 v23, v221
	v_mov_b32_e32 v24, v222
	v_mov_b32_e32 v25, v223
	s_nop 0
	v_mul_f32_e32 v0, v0, v22
	v_mul_f32_e32 v4, v4, v23
	v_cvt_pk_bf16_f32 v4, v0, v4
	v_mul_f32_e32 v0, v61, v18
	v_mul_f32_e32 v5, v5, v25
	v_mul_f32_e32 v0, v0, v24
	v_cvt_pk_bf16_f32 v5, v0, v5
	global_store_dwordx2 v[2:3], v[4:5], off offset:112
	s_nop 0
	v_mul_f32_e32 v0, v59, v18
	v_mul_f32_e32 v4, v32, v18
	v_mul_f32_e32 v5, v62, v18
	s_nop 1
	v_mov_b32_e32 v22, v224
	v_mov_b32_e32 v23, v225
	v_mov_b32_e32 v24, v226
	v_mov_b32_e32 v25, v227
	s_nop 0
	v_mul_f32_e32 v0, v0, v22
	v_mul_f32_e32 v4, v4, v23
	v_cvt_pk_bf16_f32 v4, v0, v4
	v_mul_f32_e32 v0, v63, v18
	v_mul_f32_e32 v5, v5, v25
	v_mul_f32_e32 v0, v0, v24
	v_cvt_pk_bf16_f32 v5, v0, v5
	global_store_dwordx2 v[2:3], v[4:5], off offset:128
	s_nop 0
	v_mul_f32_e32 v0, v36, v18
	v_mul_f32_e32 v4, v34, v18
	v_mul_f32_e32 v5, v84, v18
	s_nop 1
	v_mov_b32_e32 v22, v228
	v_mov_b32_e32 v23, v229
	v_mov_b32_e32 v24, v230
	v_mov_b32_e32 v25, v231
	s_nop 0
	v_mul_f32_e32 v0, v0, v22
	v_mul_f32_e32 v4, v4, v23
	v_cvt_pk_bf16_f32 v4, v0, v4
	v_mul_f32_e32 v0, v85, v18
	v_mul_f32_e32 v5, v5, v25
	v_mul_f32_e32 v0, v0, v24
	v_cvt_pk_bf16_f32 v5, v0, v5
	global_store_dwordx2 v[2:3], v[4:5], off offset:144
	s_nop 0
	v_mul_f32_e32 v0, v40, v18
	v_mul_f32_e32 v4, v39, v18
	v_mul_f32_e32 v5, v86, v18
	s_nop 1
	v_mov_b32_e32 v22, v232
	v_mov_b32_e32 v23, v233
	v_mov_b32_e32 v24, v234
	v_mov_b32_e32 v25, v235
	s_nop 0
	v_mul_f32_e32 v0, v0, v22
	v_mul_f32_e32 v4, v4, v23
	v_cvt_pk_bf16_f32 v4, v0, v4
	v_mul_f32_e32 v0, v87, v18
	v_mul_f32_e32 v5, v5, v25
	v_mul_f32_e32 v0, v0, v24
	v_cvt_pk_bf16_f32 v5, v0, v5
	global_store_dwordx2 v[2:3], v[4:5], off offset:160
	s_nop 0
	v_mul_f32_e32 v0, v44, v18
	v_mul_f32_e32 v4, v43, v18
	v_mul_f32_e32 v5, v41, v18
	s_nop 1
	v_mov_b32_e32 v22, v236
	v_mov_b32_e32 v23, v237
	v_mov_b32_e32 v24, v238
	v_mov_b32_e32 v25, v239
	s_nop 0
	v_mul_f32_e32 v0, v0, v22
	v_mul_f32_e32 v4, v4, v23
	v_cvt_pk_bf16_f32 v4, v0, v4
	v_mul_f32_e32 v0, v42, v18
	v_mul_f32_e32 v5, v5, v25
	v_mul_f32_e32 v0, v0, v24
	v_cvt_pk_bf16_f32 v5, v0, v5
	global_store_dwordx2 v[2:3], v[4:5], off offset:176
	s_nop 0
	v_mul_f32_e32 v0, v38, v18
	v_mul_f32_e32 v4, v37, v18
	v_mul_f32_e32 v5, v33, v18
	s_nop 1
	v_mov_b32_e32 v22, v244
	v_mov_b32_e32 v23, v245
	v_mov_b32_e32 v24, v246
	v_mov_b32_e32 v25, v247
	s_nop 0
	v_mul_f32_e32 v0, v0, v22
	v_mul_f32_e32 v4, v4, v23
	v_cvt_pk_bf16_f32 v4, v0, v4
	v_mul_f32_e32 v0, v35, v18
	v_mul_f32_e32 v5, v5, v25
	v_mul_f32_e32 v0, v0, v24
	v_cvt_pk_bf16_f32 v5, v0, v5
	global_store_dwordx2 v[2:3], v[4:5], off offset:192
	s_nop 0
	v_mul_f32_e32 v0, v20, v18
	v_mul_f32_e32 v4, v19, v18
	v_mul_f32_e32 v5, v15, v18
	s_nop 1
	v_mov_b32_e32 v22, v248
	v_mov_b32_e32 v23, v249
	v_mov_b32_e32 v24, v250
	v_mov_b32_e32 v25, v251
	s_nop 0
	v_mul_f32_e32 v0, v0, v22
	v_mul_f32_e32 v4, v4, v23
	v_cvt_pk_bf16_f32 v4, v0, v4
	v_mul_f32_e32 v0, v14, v18
	v_mul_f32_e32 v5, v5, v25
	v_mul_f32_e32 v0, v0, v24
	v_cvt_pk_bf16_f32 v5, v0, v5
	global_store_dwordx2 v[2:3], v[4:5], off offset:208
	s_nop 0
	v_mul_f32_e32 v0, v12, v18
	v_mul_f32_e32 v4, v13, v18
	v_mul_f32_e32 v5, v11, v18
	s_nop 1
	v_mov_b32_e32 v14, v252
	v_mov_b32_e32 v15, v253
	v_mov_b32_e32 v16, v254
	v_mov_b32_e32 v17, v255
	s_nop 0
	v_mul_f32_e32 v0, v0, v14
	v_mul_f32_e32 v4, v4, v15
	v_cvt_pk_bf16_f32 v4, v0, v4
	v_mul_f32_e32 v0, v10, v18
	v_mul_f32_e32 v5, v5, v17
	v_mul_f32_e32 v0, v0, v16
	v_cvt_pk_bf16_f32 v5, v0, v5
	global_store_dwordx2 v[2:3], v[4:5], off offset:224
	s_nop 0
	v_mul_f32_e32 v0, v8, v18
	v_mul_f32_e32 v4, v9, v18
	v_mul_f32_e32 v5, v7, v18
	s_nop 1
	v_mov_b32_e32 v10, v148
	v_mov_b32_e32 v11, v149
	v_mov_b32_e32 v12, v150
	v_mov_b32_e32 v13, v151
	s_nop 0
	v_mul_f32_e32 v0, v0, v10
	v_mul_f32_e32 v4, v4, v11
	v_cvt_pk_bf16_f32 v4, v0, v4
	v_mul_f32_e32 v0, v6, v18
	v_mul_f32_e32 v5, v5, v13
	v_mul_f32_e32 v0, v0, v12
	v_cvt_pk_bf16_f32 v5, v0, v5
	global_store_dwordx2 v[2:3], v[4:5], off offset:240
	s_branch .LBB0_198
